# remainder tiles of out-proj and ffn-down: 4-stage LDS-DMA ring GEMM (3 k-tiles in flight) replacing register-staged loops
# baseline (speedup 1.0000x reference)
; template <int MI, int NI>
; DI void gemm_kloop(const u16* Au, int lda, const u16* Bu, int ldb, int K, f32x4 (&acc)[NI][MI], unsigned char* smem) {
;   int tid_ = threadIdx.x; asm volatile("" : "+v"(tid_));
;   const int tid = tid_, lane = tid & 63, wave = tid >> 6, wm = wave >> 1, wn = wave & 1;
;   const int lr = tid >> 3, lc = tid & 7;
;   const int voa = lr * lda + lc * 8, vob = lr * ldb + lc * 8;
;   constexpr int NB2 = NI / 2;
;   u32x4 ra[MI], rb[NB2];
;   const int nk = K >> 6;
;   const int fsw = (lane & 15) >> 1;
;   const int fro0 = (lane & 15) * 128 + (((lane >> 4) ^ fsw) << 4);
;   const int fro1 = (lane & 15) * 128 + ((((lane >> 4) + 4) ^ fsw) << 4);
;   const int wof = lr * 128 + ((lc ^ ((lr >> 1) & 7)) << 4);
;     ...
;   GLOAD(0);
;   SWRITE(0);
;   if (nk > 1) GLOAD(64);
; DI void phase_resid(const Params& p, int from_x, const u16* A, int K, const u16* W, float* rowss_next, bool last,
;                     unsigned char* smem) {
;     ...
;   for (int s = vblock(); s < 4 * (NTILES - nfull); s += gridDim.x) {
;     const int it = nfull + (s >> 2), hm = s & 1, hn = (s >> 1) & 1;
;     const int g = it / (4 * NT), rem = it - g * (4 * NT), nt = rem >> 2, mt = g * 4 + (rem & 3);
;     f32x4 acc[4][2];
;     zero_acc<2, 4>(acc);
;     gemm_kloop<2, 4>(A + (size_t)(mt * 256 + hm * 128) * K, K, W + (size_t)(nt * 256 + hn * 128) * K, K, K, acc, smem);
.LBB0_231:
	s_ashr_i32 s28, s44, 2
	s_add_i32 s34, s28, s48
	s_ashr_i32 s28, s34, 31
	s_lshr_b32 s28, s28, 28
	s_add_i32 s28, s34, s28
	s_lshl_b32 s28, s28, 6
	s_and_b32 s35, s28, 0xfffffc00
	s_lshl_b32 s28, s34, 8
	s_and_b32 s28, s28, 0x300
	s_and_b32 s29, s49, 0x80
	s_or_b32 s28, s28, s29
	s_or_b32 s42, s28, s35
	s_ashr_i32 s43, s42, 31
	s_lshl_b64 s[28:29], s[42:43], 11
	s_add_u32 s28, s84, s28
	s_addc_u32 s29, s85, s29
	s_lshl_b32 s34, s34, 6
	v_mov_b32_e32 v11, v166
	s_sub_i32 s34, s34, s35
	s_and_b32 s34, s34, 0xffffff00
	s_waitcnt lgkmcnt(0)
	v_lshlrev_b32_e32 v2, 3, v11
	s_and_b32 s35, s46, 0x80
	v_ashrrev_i32_e32 v0, 3, v11
	v_and_b32_e32 v2, 56, v2
	s_or_b32 s34, s34, s35
	v_lshl_or_b32 v2, v0, 10, v2
	s_ashr_i32 s35, s34, 31
	s_waitcnt lgkmcnt(0)
	v_ashrrev_i32_e32 v3, 31, v2
	s_lshl_b64 s[52:53], s[34:35], 11
	v_lshlrev_b64 v[6:7], 1, v[2:3]
	s_add_u32 s52, s30, s52
	v_lshl_add_u64 v[2:3], s[28:29], 0, v[6:7]
	s_addc_u32 s53, s31, s53
	v_add_co_u32_e32 v4, vcc, s33, v2
	v_lshl_add_u64 v[6:7], s[52:53], 0, v[6:7]
	s_nop 0
	v_addc_co_u32_e32 v5, vcc, 0, v3, vcc
	v_add_co_u32_e32 v8, vcc, s33, v6
	s_barrier
	s_mov_b64 s[88:89], s[28:29]
	s_mov_b64 s[90:91], s[52:53]
	v_lshrrev_b32_e32 v92, 3, v166
	v_lshlrev_b32_e32 v93, 4, v166
	v_xor_b32_e32 v93, v93, v166
	v_and_b32_e32 v93, 0x70, v93
	v_lshl_or_b32 v91, v92, 11, v93
	v_lshrrev_b32_e32 v94, 6, v166
	s_nop 0
	v_readfirstlane_b32 s94, v94
	v_and_b32_e32 v92, 15, v166
	v_bfe_u32 v93, v166, 4, 2
	v_bfe_u32 v94, v166, 1, 3
	v_xor_b32_e32 v93, v93, v94
	v_lshlrev_b32_e32 v93, 4, v93
	v_lshl_or_b32 v92, v92, 7, v93
	v_lshrrev_b32_e32 v93, 7, v166
	v_lshl_or_b32 v0, v93, 12, v92
	v_bfe_u32 v94, v166, 6, 1
	v_lshl_or_b32 v47, v94, 13, v92
	v_or_b32_e32 v47, 0x4000, v47
	v_xor_b32_e32 v46, 64, v0
	v_xor_b32_e32 v86, 64, v47
	s_lshl_b32 s94, s94, 10
	s_movk_i32 s95, 15
	s_mov_b32 s32, 0
	v_mov_b32_e32 v30, 0
	v_mov_b32_e32 v31, 0
	v_mov_b32_e32 v32, 0
	v_mov_b32_e32 v33, 0
	v_mov_b32_e32 v14, 0
	v_mov_b32_e32 v15, 0
	v_mov_b32_e32 v16, 0
	v_mov_b32_e32 v17, 0
	v_mov_b32_e32 v26, 0
	v_mov_b32_e32 v27, 0
	v_mov_b32_e32 v28, 0
	v_mov_b32_e32 v29, 0
	v_mov_b32_e32 v10, 0
	v_mov_b32_e32 v11, 0
	v_mov_b32_e32 v12, 0
	v_mov_b32_e32 v13, 0
	v_mov_b32_e32 v22, 0
	v_mov_b32_e32 v23, 0
	v_mov_b32_e32 v24, 0
	v_mov_b32_e32 v25, 0
	v_mov_b32_e32 v6, 0
	v_mov_b32_e32 v7, 0
	v_mov_b32_e32 v8, 0
	v_mov_b32_e32 v9, 0
	v_mov_b32_e32 v18, 0
	v_mov_b32_e32 v19, 0
	v_mov_b32_e32 v20, 0
	v_mov_b32_e32 v21, 0
	v_mov_b32_e32 v2, 0
	v_mov_b32_e32 v3, 0
	v_mov_b32_e32 v4, 0
	v_mov_b32_e32 v5, 0
	s_add_u32 m0, s94, 0x0
	s_add_u32 s92, s88, 0x20000
	s_addc_u32 s93, s89, 0
	global_load_lds_dwordx4 v91, s[88:89]
	s_add_u32 m0, m0, 0x2000
	s_nop 0
	global_load_lds_dwordx4 v91, s[92:93]
	s_add_u32 m0, m0, 0x2000
	s_add_u32 s92, s90, 0x20000
	s_addc_u32 s93, s91, 0
	global_load_lds_dwordx4 v91, s[90:91]
	s_add_u32 m0, m0, 0x2000
	s_nop 0
	global_load_lds_dwordx4 v91, s[92:93]
	s_add_u32 s88, s88, 0x80
	s_addc_u32 s89, s89, 0
	s_add_u32 s90, s90, 0x80
	s_addc_u32 s91, s91, 0
	s_add_u32 m0, s94, 0x8000
	s_add_u32 s92, s88, 0x20000
	s_addc_u32 s93, s89, 0
	global_load_lds_dwordx4 v91, s[88:89]
	s_add_u32 m0, m0, 0x2000
	s_nop 0
	global_load_lds_dwordx4 v91, s[92:93]
	s_add_u32 m0, m0, 0x2000
	s_add_u32 s92, s90, 0x20000
	s_addc_u32 s93, s91, 0
	global_load_lds_dwordx4 v91, s[90:91]
	s_add_u32 m0, m0, 0x2000
	s_nop 0
	global_load_lds_dwordx4 v91, s[92:93]
	s_add_u32 s88, s88, 0x80
	s_addc_u32 s89, s89, 0
	s_add_u32 s90, s90, 0x80
	s_addc_u32 s91, s91, 0
	s_add_u32 m0, s94, 0x10000
	s_add_u32 s92, s88, 0x20000
	s_addc_u32 s93, s89, 0
	global_load_lds_dwordx4 v91, s[88:89]
	s_add_u32 m0, m0, 0x2000
	s_nop 0
	global_load_lds_dwordx4 v91, s[92:93]
	s_add_u32 m0, m0, 0x2000
	s_add_u32 s92, s90, 0x20000
	s_addc_u32 s93, s91, 0
	global_load_lds_dwordx4 v91, s[90:91]
	s_add_u32 m0, m0, 0x2000
	s_nop 0
	global_load_lds_dwordx4 v91, s[92:93]
	s_add_u32 s88, s88, 0x80
	s_addc_u32 s89, s89, 0
	s_add_u32 s90, s90, 0x80
	s_addc_u32 s91, s91, 0
; DI f32x4 mfma16(bf16x8 a, bf16x8 b, f32x4 c) { return __builtin_amdgcn_mfma_f32_16x16x32_bf16(a, b, c, 0, 0, 0); }
; template <int MI, int NI>
; DI void gemm_kloop(const u16* Au, int lda, const u16* Bu, int ldb, int K, f32x4 (&acc)[NI][MI], unsigned char* smem) {
;     ...
;   for (int kt = 0; kt < nk; ++kt) {
;     __syncthreads();
;     if (kt + 1 < nk) {
;       SWRITE((kt + 1) & 1);
;       if (kt + 2 < nk) GLOAD((kt + 2) << 6);
;     }
;     {
;       const unsigned char* sa = smem + (kt & 1) * 65536;
;       const unsigned char* sb = sa + 32768;
; #pragma unroll
;       for (int ks = 0; ks < 2; ++ks) {
;         const int fo = ks ? fro1 : fro0;
;         bf16x8 af[MI];
; #pragma unroll
;         for (int i = 0; i < MI; ++i) af[i] = *(const bf16x8*)(sa + (wm * 16 * MI + i * 16) * 128 + fo);
; #pragma unroll
;         for (int nh = 0; nh < NI; nh += 4) {
;           bf16x8 wf[4];
; #pragma unroll
;           for (int i = 0; i < 4; ++i) wf[i] = *(const bf16x8*)(sb + (wn * 16 * NI + (nh + i) * 16) * 128 + fo);
; #pragma unroll
;           for (int ni = 0; ni < 4; ++ni)
; #pragma unroll
;             for (int mi = 0; mi < MI; ++mi) acc[nh + ni][mi] = mfma16(wf[ni], af[mi], acc[nh + ni][mi]);
;         }
;       }
;     }
;   }
; template <int MI, int NI>
; DI void resid_epilogue(const Params& p, int from_x, const f32x4 (&acc)[NI][MI], int row0, int n0, float* rowss_next, bool last, int lm, int lg) {
; #pragma unroll
;   for (int mi = 0; mi < MI; ++mi) {
;     const int m = row0 + mi * 16 + lm;
;     const float* hr = hrow_r(p, from_x == 1 ? 0 : 1, m);
;     float* hw = hrow_w(p, m);
;     u16* hbr = p.hb + (size_t)m * DM;
.Lrem_outproj_loop:
	s_cmp_gt_u32 s95, 1
	s_cbranch_scc1 .Lrem_outproj_w8
	s_cmp_eq_u32 s95, 1
	s_cbranch_scc1 .Lrem_outproj_w4
	s_waitcnt vmcnt(0)
	s_branch .Lrem_outproj_bar
.Lrem_outproj_w4:
	s_waitcnt vmcnt(4)
	s_branch .Lrem_outproj_bar
.Lrem_outproj_w8:
	s_waitcnt vmcnt(8)
.Lrem_outproj_bar:
	s_barrier
	s_cmp_gt_u32 s95, 2
	s_cbranch_scc0 .Lrem_outproj_nodma
	s_add_u32 m0, s32, 0x18000
	s_and_b32 m0, m0, 0x18000
	s_add_u32 m0, m0, s94
	s_add_u32 s92, s88, 0x20000
	s_addc_u32 s93, s89, 0
	global_load_lds_dwordx4 v91, s[88:89]
	s_add_u32 m0, m0, 0x2000
	s_nop 0
	global_load_lds_dwordx4 v91, s[92:93]
	s_add_u32 m0, m0, 0x2000
	s_add_u32 s92, s90, 0x20000
	s_addc_u32 s93, s91, 0
	global_load_lds_dwordx4 v91, s[90:91]
	s_add_u32 m0, m0, 0x2000
	s_nop 0
	global_load_lds_dwordx4 v91, s[92:93]
	s_add_u32 s88, s88, 0x80
	s_addc_u32 s89, s89, 0
	s_add_u32 s90, s90, 0x80
	s_addc_u32 s91, s91, 0
.Lrem_outproj_nodma:
	v_add_u32_e32 v87, s32, v0
	v_add_u32_e32 v89, s32, v47
	v_add_u32_e32 v88, s32, v46
	v_add_u32_e32 v90, s32, v86
	ds_read_b128 v[34:37], v87
	ds_read_b128 v[38:41], v87 offset:2048
	ds_read_b128 v[54:57], v89
	ds_read_b128 v[58:61], v89 offset:2048
	ds_read_b128 v[62:65], v89 offset:4096
	ds_read_b128 v[66:69], v89 offset:6144
	ds_read_b128 v[42:45], v88
	ds_read_b128 v[50:53], v88 offset:2048
	ds_read_b128 v[70:73], v90
	ds_read_b128 v[74:77], v90 offset:2048
	ds_read_b128 v[78:81], v90 offset:4096
	ds_read_b128 v[82:85], v90 offset:6144
	s_waitcnt lgkmcnt(9)
	v_mfma_f32_16x16x32_bf16 v[30:33], v[54:57], v[34:37], v[30:33]
	v_mfma_f32_16x16x32_bf16 v[14:17], v[54:57], v[38:41], v[14:17]
	s_waitcnt lgkmcnt(8)
	v_mfma_f32_16x16x32_bf16 v[26:29], v[58:61], v[34:37], v[26:29]
	v_mfma_f32_16x16x32_bf16 v[10:13], v[58:61], v[38:41], v[10:13]
	s_waitcnt lgkmcnt(7)
	v_mfma_f32_16x16x32_bf16 v[22:25], v[62:65], v[34:37], v[22:25]
	v_mfma_f32_16x16x32_bf16 v[6:9], v[62:65], v[38:41], v[6:9]
	s_waitcnt lgkmcnt(6)
	v_mfma_f32_16x16x32_bf16 v[18:21], v[66:69], v[34:37], v[18:21]
	v_mfma_f32_16x16x32_bf16 v[2:5], v[66:69], v[38:41], v[2:5]
	s_waitcnt lgkmcnt(3)
	v_mfma_f32_16x16x32_bf16 v[30:33], v[70:73], v[42:45], v[30:33]
	v_mfma_f32_16x16x32_bf16 v[14:17], v[70:73], v[50:53], v[14:17]
	s_waitcnt lgkmcnt(2)
	v_mfma_f32_16x16x32_bf16 v[26:29], v[74:77], v[42:45], v[26:29]
	v_mfma_f32_16x16x32_bf16 v[10:13], v[74:77], v[50:53], v[10:13]
	s_waitcnt lgkmcnt(1)
	v_mfma_f32_16x16x32_bf16 v[22:25], v[78:81], v[42:45], v[22:25]
	v_mfma_f32_16x16x32_bf16 v[6:9], v[78:81], v[50:53], v[6:9]
	s_waitcnt lgkmcnt(0)
	v_mfma_f32_16x16x32_bf16 v[18:21], v[82:85], v[42:45], v[18:21]
	v_mfma_f32_16x16x32_bf16 v[2:5], v[82:85], v[50:53], v[2:5]
	s_add_u32 s32, s32, 0x8000
	s_and_b32 s32, s32, 0x18000
	s_add_i32 s95, s95, -1
	s_cmp_ge_i32 s95, 0
	s_cbranch_scc1 .Lrem_outproj_loop
	s_nop 7
	s_nop 7
	v_add_u32_e32 v40, s42, v48
	v_mul_hi_i32 v0, v40, s81
	v_lshrrev_b32_e32 v35, 31, v0
	v_ashrrev_i32_e32 v0, 10, v0
	v_add_u32_e32 v0, v0, v35
	v_mad_i32_i24 v34, v0, s82, v40
	v_add_u32_e32 v36, -16, v34
	v_cmp_lt_u32_e32 vcc, s83, v36
	s_and_saveexec_b64 s[28:29], vcc
	s_xor_b64 s[28:29], exec, s[28:29]
	v_add_u32_e32 v35, 0xfffff000, v34
	v_cmp_gt_i32_e32 vcc, 16, v34
	s_nop 1
	v_cndmask_b32_e32 v34, v35, v34, vcc
	v_lshl_add_u32 v44, v0, 7, v34
	s_or_saveexec_b64 s[28:29], s[28:29]
	v_mov_b64_e32 v[34:35], s[96:97]
	s_xor_b64 exec, exec, s[28:29]
	v_lshl_add_u32 v44, v0, 12, v36
	v_mov_b64_e32 v[34:35], s[2:3]
	s_or_b64 exec, exec, s[28:29]
	global_load_dwordx2 v[46:47], v[34:35], off
	s_load_dwordx16 s[52:67], s[0:1], 0xc8
	v_ashrrev_i32_e32 v41, 31, v40
	v_or_b32_e32 v38, s34, v49
	v_lshlrev_b64 v[34:35], 11, v[40:41]
	v_ashrrev_i32_e32 v39, 31, v38
	s_waitcnt lgkmcnt(0)
	v_lshl_add_u64 v[34:35], s[52:53], 0, v[34:35]
	s_mov_b64 s[28:29], -1
	s_andn2_b64 vcc, exec, s[4:5]
	v_lshl_add_u64 v[42:43], v[38:39], 1, v[34:35]
	s_cbranch_vccnz .LBB0_237
	global_load_dwordx2 v[36:37], v[42:43], off
	s_mov_b64 s[28:29], 0
	s_waitcnt vmcnt(0)
	v_and_b32_e32 v35, 0xffff0000, v36
	v_lshlrev_b32_e32 v34, 16, v36
	v_lshlrev_b32_e32 v36, 16, v37
	v_and_b32_e32 v37, 0xffff0000, v37

; template <int MI, int NI>
; DI void gemm_kloop(const u16* Au, int lda, const u16* Bu, int ldb, int K, f32x4 (&acc)[NI][MI], unsigned char* smem) {
;   int tid_ = threadIdx.x; asm volatile("" : "+v"(tid_));
;   const int tid = tid_, lane = tid & 63, wave = tid >> 6, wm = wave >> 1, wn = wave & 1;
;   const int lr = tid >> 3, lc = tid & 7;
;   const int voa = lr * lda + lc * 8, vob = lr * ldb + lc * 8;
;   constexpr int NB2 = NI / 2;
;   u32x4 ra[MI], rb[NB2];
;   const int nk = K >> 6;
;   const int fsw = (lane & 15) >> 1;
;   const int fro0 = (lane & 15) * 128 + (((lane >> 4) ^ fsw) << 4);
;   const int fro1 = (lane & 15) * 128 + ((((lane >> 4) + 4) ^ fsw) << 4);
;   const int wof = lr * 128 + ((lc ^ ((lr >> 1) & 7)) << 4);
;     ...
;   GLOAD(0);
;   SWRITE(0);
;   if (nk > 1) GLOAD(64);
; DI void phase_resid(const Params& p, int from_x, const u16* A, int K, const u16* W, float* rowss_next, bool last,
;                     unsigned char* smem) {
;     ...
;   for (int s = vblock(); s < 4 * (NTILES - nfull); s += gridDim.x) {
;     const int it = nfull + (s >> 2), hm = s & 1, hn = (s >> 1) & 1;
;     const int g = it / (4 * NT), rem = it - g * (4 * NT), nt = rem >> 2, mt = g * 4 + (rem & 3);
;     f32x4 acc[4][2];
;     zero_acc<2, 4>(acc);
;     gemm_kloop<2, 4>(A + (size_t)(mt * 256 + hm * 128) * K, K, W + (size_t)(nt * 256 + hn * 128) * K, K, K, acc, smem);
.LBB0_1126:
	s_ashr_i32 s2, s8, 2
	s_add_i32 s42, s2, s30
	s_ashr_i32 s2, s42, 31
	s_lshr_b32 s2, s2, 28
	s_add_i32 s2, s42, s2
	s_lshl_b32 s2, s2, 6
	s_and_b32 s49, s2, 0xfffffc00
	s_lshl_b32 s2, s42, 8
	s_and_b32 s50, s2, 0x300
	s_lshl_b32 s2, s8, 7
	s_and_b32 s2, s2, 0x80
	s_or_b32 s2, s50, s2
	s_or_b32 s43, s2, s49
	s_and_b32 s45, s31, 0x80
	s_and_b32 s48, s35, 0x80
	s_mul_i32 s2, s43, 0x1600
	s_mul_hi_i32 s3, s43, 0x1600
	s_add_u32 s2, s86, s2
	s_waitcnt vmcnt(2)
	v_mov_b32_e32 v38, v166
	s_addc_u32 s3, s87, s3
	s_lshl_b32 s42, s42, 6
	s_movk_i32 s52, 0xb00
	v_ashrrev_i32_e32 v39, 3, v38
	s_sub_i32 s42, s42, s49
	v_mul_lo_u32 v2, v39, s52
	s_waitcnt lgkmcnt(0)
	v_lshlrev_b32_e32 v3, 3, v38
	s_and_b32 s51, s42, 0xffffff00
	s_lshl_b32 s42, s8, 6
	v_and_or_b32 v2, v3, 56, v2
	s_and_b32 s42, s42, 0x80
	v_ashrrev_i32_e32 v3, 31, v2
	s_or_b32 s42, s51, s42
	v_lshlrev_b64 v[4:5], 1, v[2:3]
	s_mul_i32 s46, s42, 0x1600
	v_lshl_add_u64 v[2:3], s[2:3], 0, v[4:5]
	s_mul_hi_i32 s47, s42, 0x1600
	s_add_u32 s46, s28, s46
	v_add_co_u32_e32 v10, vcc, s24, v2
	s_addc_u32 s47, s29, s47
	s_mov_b64 s[88:89], s[2:3]
	s_mov_b64 s[90:91], s[46:47]
	v_addc_co_u32_e32 v11, vcc, 0, v3, vcc
	s_nop 0
	v_lshl_add_u64 v[6:7], s[46:47], 0, v[4:5]
	s_nop 0
	v_add_co_u32_e32 v18, vcc, s24, v6
	s_or_b32 s45, s51, s45
	s_nop 0
	v_addc_co_u32_e32 v19, vcc, 0, v7, vcc
	s_nop 0
	s_nop 0
	s_nop 0
	s_nop 0
	s_nop 0
	s_nop 0
	s_nop 0
	s_nop 0
	s_nop 0
	s_mul_hi_i32 s47, s45, 0x1600
	s_mulk_i32 s45, 0x1600
	s_add_u32 s46, s23, s45
	s_addc_u32 s47, s21, s47
	s_or_b32 s45, s49, s50
	s_or_b32 s45, s45, s48
	v_and_b32_e32 v40, 15, v38
	v_bfe_u32 v41, v38, 1, 3
	s_waitcnt vmcnt(9)
	v_lshrrev_b32_e32 v42, 4, v38
	v_bfe_u32 v43, v38, 4, 2
	v_lshlrev_b32_e32 v44, 4, v38
	v_lshl_add_u64 v[50:51], s[46:47], 0, v[4:5]
	s_mul_hi_i32 s47, s45, 0x1600
	s_mulk_i32 s45, 0x1600
	v_lshlrev_b32_e32 v45, 5, v38
	s_waitcnt vmcnt(8)
	v_lshlrev_b32_e32 v46, 7, v38
	v_xor_b32_e32 v38, v44, v38
	v_lshlrev_b32_e32 v39, 7, v39
	v_lshlrev_b32_e32 v56, 7, v40
	v_bitop3_b32 v40, v42, v41, 3 bitop3:0x6c
	v_bitop3_b32 v41, v43, v41, 4 bitop3:0x36
	s_add_u32 s46, s86, s45
	v_mov_b32_e32 v2, 0
	v_and_b32_e32 v60, 0xfffff000, v45
	v_and_b32_e32 v65, 0x2000, v46
	v_and_or_b32 v66, v38, s12, v39
	v_lshlrev_b32_e32 v57, 4, v40
	v_lshlrev_b32_e32 v55, 4, v41
	s_addc_u32 s47, s87, s47
	s_mov_b64 s[2:3], 0
	v_mov_b32_e32 v3, v2
	v_add_u32_e32 v58, 0x10000, v60
	v_or_b32_e32 v59, 0x18000, v65
	v_or_b32_e32 v67, v57, v56
	v_or_b32_e32 v68, v55, v56
	v_add_u32_e32 v61, 0x10000, v66
	v_add_u32_e32 v62, 0x12000, v66
	v_add_u32_e32 v63, 0x18000, v66
	v_add_u32_e32 v64, 0x1a000, v66
	v_lshl_add_u64 v[52:53], s[46:47], 0, v[4:5]
	v_mov_b32_e32 v4, v2
	v_mov_b32_e32 v5, v2
	v_mov_b32_e32 v38, v2
	v_mov_b32_e32 v39, v2
	v_mov_b32_e32 v40, v2
	v_mov_b32_e32 v41, v2
	v_mov_b32_e32 v42, v2
	s_waitcnt vmcnt(7)
	s_nop 0
	s_waitcnt vmcnt(6)
	s_nop 0
	s_waitcnt vmcnt(5)
	s_nop 0
	s_waitcnt vmcnt(4)
	s_nop 0
	v_mov_b32_e32 v22, v2
	v_mov_b32_e32 v23, v2
	v_mov_b32_e32 v24, v2
	v_mov_b32_e32 v25, v2
	v_mov_b32_e32 v26, v2
	v_mov_b32_e32 v27, v2
	v_mov_b32_e32 v28, v2
	v_mov_b32_e32 v29, v2
	v_mov_b32_e32 v30, v2
	v_mov_b32_e32 v31, v2
	v_mov_b32_e32 v32, v2
	v_mov_b32_e32 v33, v2
	v_mov_b32_e32 v34, v2
	v_mov_b32_e32 v35, v2
	v_mov_b32_e32 v36, v2
	v_mov_b32_e32 v37, v2
	v_mov_b32_e32 v43, v2
	v_mov_b32_e32 v44, v2
	v_mov_b32_e32 v45, v2
	v_mov_b32_e32 v46, v2
	v_mov_b32_e32 v47, v2
	v_mov_b32_e32 v48, v2
	v_mov_b32_e32 v49, v2
	s_barrier
	s_mov_b64 s[88:89], s[88:89]
	s_mov_b64 s[90:91], s[90:91]
	v_lshrrev_b32_e32 v92, 3, v166
	v_lshlrev_b32_e32 v93, 4, v166
	v_xor_b32_e32 v93, v93, v166
	v_and_b32_e32 v93, 0x70, v93
	v_mul_u32_u24_e32 v91, 0x1600, v92
	v_or_b32_e32 v91, v91, v93
	v_lshrrev_b32_e32 v94, 6, v166
	s_nop 0
	v_readfirstlane_b32 s94, v94
	v_and_b32_e32 v92, 15, v166
	v_bfe_u32 v93, v166, 4, 2
	v_bfe_u32 v94, v166, 1, 3
	v_xor_b32_e32 v93, v93, v94
	v_lshlrev_b32_e32 v93, 4, v93
	v_lshl_or_b32 v92, v92, 7, v93
	v_lshrrev_b32_e32 v93, 7, v166
	v_lshl_or_b32 v55, v93, 12, v92
	v_bfe_u32 v94, v166, 6, 1
	v_lshl_or_b32 v85, v94, 13, v92
	v_or_b32_e32 v85, 0x4000, v85
	v_xor_b32_e32 v84, 64, v55
	v_xor_b32_e32 v86, 64, v85
	s_lshl_b32 s94, s94, 10
	s_movk_i32 s95, 43
	s_mov_b32 s32, 0
	v_mov_b32_e32 v30, 0
	v_mov_b32_e32 v31, 0
	v_mov_b32_e32 v32, 0
	v_mov_b32_e32 v33, 0
	v_mov_b32_e32 v14, 0
	v_mov_b32_e32 v15, 0
	v_mov_b32_e32 v16, 0
	v_mov_b32_e32 v17, 0
	v_mov_b32_e32 v26, 0
	v_mov_b32_e32 v27, 0
	v_mov_b32_e32 v28, 0
	v_mov_b32_e32 v29, 0
	v_mov_b32_e32 v10, 0
	v_mov_b32_e32 v11, 0
	v_mov_b32_e32 v12, 0
	v_mov_b32_e32 v13, 0
	v_mov_b32_e32 v22, 0
	v_mov_b32_e32 v23, 0
	v_mov_b32_e32 v24, 0
	v_mov_b32_e32 v25, 0
	v_mov_b32_e32 v6, 0
	v_mov_b32_e32 v7, 0
	v_mov_b32_e32 v8, 0
	v_mov_b32_e32 v9, 0
	v_mov_b32_e32 v18, 0
	v_mov_b32_e32 v19, 0
	v_mov_b32_e32 v20, 0
	v_mov_b32_e32 v21, 0
	v_mov_b32_e32 v2, 0
	v_mov_b32_e32 v3, 0
	v_mov_b32_e32 v4, 0
	v_mov_b32_e32 v5, 0
	s_add_u32 m0, s94, 0x0
	s_add_u32 s92, s88, 0x58000
	s_addc_u32 s93, s89, 0
	global_load_lds_dwordx4 v91, s[88:89]
	s_add_u32 m0, m0, 0x2000
	s_nop 0
	global_load_lds_dwordx4 v91, s[92:93]
	s_add_u32 m0, m0, 0x2000
	s_add_u32 s92, s90, 0x58000
	s_addc_u32 s93, s91, 0
	global_load_lds_dwordx4 v91, s[90:91]
	s_add_u32 m0, m0, 0x2000
	s_nop 0
	global_load_lds_dwordx4 v91, s[92:93]
	s_add_u32 s88, s88, 0x80
	s_addc_u32 s89, s89, 0
	s_add_u32 s90, s90, 0x80
	s_addc_u32 s91, s91, 0
	s_add_u32 m0, s94, 0x8000
	s_add_u32 s92, s88, 0x58000
	s_addc_u32 s93, s89, 0
	global_load_lds_dwordx4 v91, s[88:89]
	s_add_u32 m0, m0, 0x2000
	s_nop 0
	global_load_lds_dwordx4 v91, s[92:93]
	s_add_u32 m0, m0, 0x2000
	s_add_u32 s92, s90, 0x58000
	s_addc_u32 s93, s91, 0
	global_load_lds_dwordx4 v91, s[90:91]
	s_add_u32 m0, m0, 0x2000
	s_nop 0
	global_load_lds_dwordx4 v91, s[92:93]
	s_add_u32 s88, s88, 0x80
	s_addc_u32 s89, s89, 0
	s_add_u32 s90, s90, 0x80
	s_addc_u32 s91, s91, 0
	s_add_u32 m0, s94, 0x10000
	s_add_u32 s92, s88, 0x58000
	s_addc_u32 s93, s89, 0
	global_load_lds_dwordx4 v91, s[88:89]
	s_add_u32 m0, m0, 0x2000
	s_nop 0
	global_load_lds_dwordx4 v91, s[92:93]
	s_add_u32 m0, m0, 0x2000
	s_add_u32 s92, s90, 0x58000
	s_addc_u32 s93, s91, 0
	global_load_lds_dwordx4 v91, s[90:91]
	s_add_u32 m0, m0, 0x2000
	s_nop 0
	global_load_lds_dwordx4 v91, s[92:93]
	s_add_u32 s88, s88, 0x80
	s_addc_u32 s89, s89, 0
	s_add_u32 s90, s90, 0x80
	s_addc_u32 s91, s91, 0

; DI f32x4 mfma16(bf16x8 a, bf16x8 b, f32x4 c) { return __builtin_amdgcn_mfma_f32_16x16x32_bf16(a, b, c, 0, 0, 0); }
; template <int MI, int NI>
; DI void gemm_kloop(const u16* Au, int lda, const u16* Bu, int ldb, int K, f32x4 (&acc)[NI][MI], unsigned char* smem) {
;     ...
;   for (int kt = 0; kt < nk; ++kt) {
;     __syncthreads();
;     if (kt + 1 < nk) {
;       SWRITE((kt + 1) & 1);
;       if (kt + 2 < nk) GLOAD((kt + 2) << 6);
;     }
;     {
;       const unsigned char* sa = smem + (kt & 1) * 65536;
;       const unsigned char* sb = sa + 32768;
; #pragma unroll
;       for (int ks = 0; ks < 2; ++ks) {
;         const int fo = ks ? fro1 : fro0;
;         bf16x8 af[MI];
; #pragma unroll
;         for (int i = 0; i < MI; ++i) af[i] = *(const bf16x8*)(sa + (wm * 16 * MI + i * 16) * 128 + fo);
; #pragma unroll
;         for (int nh = 0; nh < NI; nh += 4) {
;           bf16x8 wf[4];
; #pragma unroll
;           for (int i = 0; i < 4; ++i) wf[i] = *(const bf16x8*)(sb + (wn * 16 * NI + (nh + i) * 16) * 128 + fo);
; #pragma unroll
;           for (int ni = 0; ni < 4; ++ni)
; #pragma unroll
;             for (int mi = 0; mi < MI; ++mi) acc[nh + ni][mi] = mfma16(wf[ni], af[mi], acc[nh + ni][mi]);
;         }
;       }
;     }
;   }
; template <int MI, int NI>
; DI void resid_epilogue(const Params& p, int from_x, const f32x4 (&acc)[NI][MI], int row0, int n0, float* rowss_next, bool last, int lm, int lg) {
; #pragma unroll
;   for (int mi = 0; mi < MI; ++mi) {
;     const int m = row0 + mi * 16 + lm;
;     const float* hr = hrow_r(p, from_x == 1 ? 0 : 1, m);
;     float* hw = hrow_w(p, m);
;     u16* hbr = p.hb + (size_t)m * DM;
.Lrem_down_bar:
	s_barrier
	s_cmp_gt_u32 s95, 2
	s_cbranch_scc0 .Lrem_down_nodma
	s_add_u32 m0, s32, 0x18000
	s_and_b32 m0, m0, 0x18000
	s_add_u32 m0, m0, s94
	s_add_u32 s92, s88, 0x58000
	s_addc_u32 s93, s89, 0
	global_load_lds_dwordx4 v91, s[88:89]
	s_add_u32 m0, m0, 0x2000
	s_nop 0
	global_load_lds_dwordx4 v91, s[92:93]
	s_add_u32 m0, m0, 0x2000
	s_add_u32 s92, s90, 0x58000
	s_addc_u32 s93, s91, 0
	global_load_lds_dwordx4 v91, s[90:91]
	s_add_u32 m0, m0, 0x2000
	s_nop 0
	global_load_lds_dwordx4 v91, s[92:93]
	s_add_u32 s88, s88, 0x80
	s_addc_u32 s89, s89, 0
	s_add_u32 s90, s90, 0x80
	s_addc_u32 s91, s91, 0
.Lrem_down_nodma:
	v_add_u32_e32 v87, s32, v55
	v_add_u32_e32 v89, s32, v85
	v_add_u32_e32 v88, s32, v84
	v_add_u32_e32 v90, s32, v86
	ds_read_b128 v[34:37], v87
	ds_read_b128 v[38:41], v87 offset:2048
	ds_read_b128 v[50:53], v89
	ds_read_b128 v[56:59], v89 offset:2048
	ds_read_b128 v[60:63], v89 offset:4096
	ds_read_b128 v[64:67], v89 offset:6144
	ds_read_b128 v[42:45], v88
	ds_read_b128 v[46:49], v88 offset:2048
	ds_read_b128 v[68:71], v90
	ds_read_b128 v[72:75], v90 offset:2048
	ds_read_b128 v[76:79], v90 offset:4096
	ds_read_b128 v[80:83], v90 offset:6144
	s_waitcnt lgkmcnt(9)
	v_mfma_f32_16x16x32_bf16 v[30:33], v[50:53], v[34:37], v[30:33]
	v_mfma_f32_16x16x32_bf16 v[14:17], v[50:53], v[38:41], v[14:17]
	s_waitcnt lgkmcnt(8)
	v_mfma_f32_16x16x32_bf16 v[26:29], v[56:59], v[34:37], v[26:29]
	v_mfma_f32_16x16x32_bf16 v[10:13], v[56:59], v[38:41], v[10:13]
	s_waitcnt lgkmcnt(7)
	v_mfma_f32_16x16x32_bf16 v[22:25], v[60:63], v[34:37], v[22:25]
	v_mfma_f32_16x16x32_bf16 v[6:9], v[60:63], v[38:41], v[6:9]
	s_waitcnt lgkmcnt(6)
	v_mfma_f32_16x16x32_bf16 v[18:21], v[64:67], v[34:37], v[18:21]
	v_mfma_f32_16x16x32_bf16 v[2:5], v[64:67], v[38:41], v[2:5]
	s_waitcnt lgkmcnt(3)
	v_mfma_f32_16x16x32_bf16 v[30:33], v[68:71], v[42:45], v[30:33]
	v_mfma_f32_16x16x32_bf16 v[14:17], v[68:71], v[46:49], v[14:17]
	s_waitcnt lgkmcnt(2)
	v_mfma_f32_16x16x32_bf16 v[26:29], v[72:75], v[42:45], v[26:29]
	v_mfma_f32_16x16x32_bf16 v[10:13], v[72:75], v[46:49], v[10:13]
	s_waitcnt lgkmcnt(1)
	v_mfma_f32_16x16x32_bf16 v[22:25], v[76:79], v[42:45], v[22:25]
	v_mfma_f32_16x16x32_bf16 v[6:9], v[76:79], v[46:49], v[6:9]
	s_waitcnt lgkmcnt(0)
	v_mfma_f32_16x16x32_bf16 v[18:21], v[80:83], v[42:45], v[18:21]
	v_mfma_f32_16x16x32_bf16 v[2:5], v[80:83], v[46:49], v[2:5]
	s_add_u32 s32, s32, 0x8000
	s_and_b32 s32, s32, 0x18000
	s_add_i32 s95, s95, -1
	s_cmp_ge_i32 s95, 0
	s_cbranch_scc1 .Lrem_down_loop
	s_nop 7
	s_nop 7
	v_add_u32_e32 v34, s43, v0
	v_mul_hi_i32 v38, v34, s81
	v_lshrrev_b32_e32 v35, 31, v38
	v_ashrrev_i32_e32 v40, 10, v38
	v_add_u32_e32 v35, v40, v35
	v_mad_i32_i24 v37, v35, s82, v34
	v_add_u32_e32 v36, -16, v37
	v_cmp_lt_u32_e32 vcc, s83, v36
	s_and_saveexec_b64 s[2:3], vcc
	s_xor_b64 s[2:3], exec, s[2:3]
	v_add_u32_e32 v36, 0xfffff000, v37
	v_cmp_gt_i32_e32 vcc, 16, v37
	s_nop 1
	v_cndmask_b32_e32 v36, v36, v37, vcc
	v_lshl_add_u32 v40, v35, 7, v36
	s_or_saveexec_b64 s[2:3], s[2:3]
	v_mov_b64_e32 v[38:39], s[96:97]
	s_xor_b64 exec, exec, s[2:3]
	s_cbranch_execz .LBB0_1132
	v_readlane_b32 s46, v253, 27
	v_readlane_b32 s47, v253, 28
	v_lshl_add_u32 v40, v35, 12, v36
	s_nop 0
	v_mov_b64_e32 v[38:39], s[46:47]
